# phase-2 in-proj GEMM: per-XCD tile order changed to 8 token blocks x 8 columns per round (tb=lt&7, col=lt>>3) for L2 reuse of W
# baseline (speedup 1.0000x reference)
.LBB0_237:
	s_and_b32 s0, s2, 7
	s_add_i32 s4, s0, s24
	v_mov_b32_e32 v48, v207
	s_lshl_b32 s5, s4, 8
	s_nop 0
	v_ashrrev_i32_e32 v49, 3, v48
	v_add_u32_e32 v0, s5, v49
	s_waitcnt lgkmcnt(0)
	v_ashrrev_i32_e32 v1, 31, v0
	v_lshlrev_b64 v[0:1], 11, v[0:1]
	v_lshlrev_b32_e32 v4, 4, v48
	v_and_b32_e32 v160, 0x70, v4
	v_lshl_add_u64 v[0:1], s[6:7], 0, v[0:1]
	v_lshl_add_u64 v[130:131], v[0:1], 0, v[160:161]
	v_add_co_u32_e32 v0, vcc, s33, v130
	s_lshr_b32 s0, s2, 3
	s_nop 0
	v_addc_co_u32_e32 v1, vcc, 0, v131, vcc
	v_add_co_u32_e32 v4, vcc, s37, v130
	s_and_b32 s1, s4, 1
	s_mov_b32 s1, 0
	s_add_i32 s0, s0, s1
	s_add_i32 s1, s0, -24
	s_cmpk_ge_i32 s0, 24
	s_cselect_b32 s0, s1, s0
	s_lshl_b32 s40, s0, 7
	s_nop 0
	v_addc_co_u32_e32 v5, vcc, 0, v131, vcc
	v_add_co_u32_e32 v8, vcc, s39, v130
	v_add_u32_e32 v2, s40, v49
	s_nop 0
	v_addc_co_u32_e32 v9, vcc, 0, v131, vcc
	v_add_co_u32_e32 v12, vcc, s66, v130
	v_ashrrev_i32_e32 v3, 31, v2
	s_nop 0
	v_addc_co_u32_e32 v13, vcc, 0, v131, vcc
	v_add_co_u32_e32 v16, vcc, s67, v130
	v_lshlrev_b64 v[2:3], 11, v[2:3]
	s_nop 0
	v_addc_co_u32_e32 v17, vcc, 0, v131, vcc
	v_add_co_u32_e32 v20, vcc, s68, v130
	v_lshl_add_u64 v[2:3], s[58:59], 0, v[2:3]
	s_nop 0
	v_addc_co_u32_e32 v21, vcc, 0, v131, vcc
	v_add_co_u32_e32 v32, vcc, s69, v130
	v_lshl_add_u64 v[128:129], v[2:3], 0, v[160:161]
	s_nop 0
	v_addc_co_u32_e32 v33, vcc, 0, v131, vcc
	v_add_co_u32_e32 v36, vcc, s33, v128
	global_load_dwordx4 v[0:3], v[0:1], off
	s_nop 0
	global_load_dwordx4 v[4:7], v[4:5], off
	v_addc_co_u32_e32 v37, vcc, 0, v129, vcc
	v_add_co_u32_e32 v40, vcc, s37, v128
	global_load_dwordx4 v[8:11], v[8:9], off
	s_nop 0
	global_load_dwordx4 v[12:15], v[12:13], off
	v_addc_co_u32_e32 v41, vcc, 0, v129, vcc
	v_add_co_u32_e32 v44, vcc, s39, v128
	global_load_dwordx4 v[16:19], v[16:17], off
	s_nop 0
	global_load_dwordx4 v[20:23], v[20:21], off
	v_addc_co_u32_e32 v45, vcc, 0, v129, vcc
	global_load_dwordx4 v[24:27], v[130:131], off
	global_load_dwordx4 v[28:31], v[128:129], off
	s_nop 0
	global_load_dwordx4 v[32:35], v[32:33], off
	s_nop 0
	global_load_dwordx4 v[36:39], v[36:37], off
	s_nop 0
	global_load_dwordx4 v[40:43], v[40:41], off
	s_nop 0
	global_load_dwordx4 v[44:47], v[44:45], off
	v_lshrrev_b32_e32 v50, 5, v48
	v_ashrrev_i32_e32 v51, 4, v48
	v_xor_b32_e32 v53, v50, v48
	v_lshlrev_b32_e32 v54, 12, v49
	v_xor_b32_e32 v52, v51, v48
	v_lshlrev_b32_e32 v53, 4, v53
	v_and_b32_e32 v54, 0x1000, v54
	v_lshlrev_b32_e32 v52, 4, v52
	v_and_b32_e32 v53, 0x70, v53
	v_lshl_add_u32 v51, v51, 7, v54
	v_and_b32_e32 v52, 0x70, v52
	v_lshlrev_b32_e32 v49, 7, v49
	v_or_b32_e32 v54, v51, v53
	v_bfe_u32 v187, v48, 5, 1
	v_bfe_u32 v132, v48, 6, 1
	v_ashrrev_i32_e32 v133, 7, v48
	v_and_b32_e32 v188, 31, v48
	v_add_u32_e32 v142, v51, v53
	v_add_u32_e32 v143, v52, v49
	s_mov_b32 s41, 64
	v_mov_b32_e32 v96, 0
	v_mov_b32_e32 v97, v161
	v_mov_b32_e32 v98, v161
	v_mov_b32_e32 v99, v161
	v_mov_b32_e32 v100, v161
	v_mov_b32_e32 v101, v161
	v_mov_b32_e32 v102, v161
	v_mov_b32_e32 v103, v161
	v_mov_b32_e32 v104, v161
	v_mov_b32_e32 v105, v161
	v_mov_b32_e32 v106, v161
	v_mov_b32_e32 v107, v161
	v_mov_b32_e32 v108, v161
	v_mov_b32_e32 v109, v161
	v_mov_b32_e32 v110, v161
	s_waitcnt vmcnt(5)
	ds_write_b128 v54, v[24:27]
	ds_write_b128 v54, v[0:3] offset:2048
	ds_write_b128 v54, v[4:7] offset:8192
	ds_write_b128 v54, v[8:11] offset:10240
	ds_write_b128 v54, v[12:15] offset:16384
	ds_write_b128 v54, v[16:19] offset:18432
	ds_write_b128 v54, v[20:23] offset:24576
	s_waitcnt vmcnt(3)
	ds_write_b128 v54, v[32:35] offset:26624
	v_or_b32_e32 v0, v52, v49
	ds_write_b128 v0, v[28:31] offset:32768
	s_waitcnt vmcnt(2)
	ds_write_b128 v0, v[36:39] offset:36864
	s_waitcnt vmcnt(1)
	ds_write_b128 v0, v[40:43] offset:40960
	s_waitcnt vmcnt(0)
	ds_write_b128 v0, v[44:47] offset:45056
	v_bfe_u32 v0, v48, 1, 3
	v_bitop3_b32 v1, v50, v0, 1 bitop3:0x6c
	v_bitop3_b32 v6, v187, v0, 2 bitop3:0x36
	v_bitop3_b32 v8, v187, v0, 4 bitop3:0x36
	v_bitop3_b32 v0, v187, v0, 6 bitop3:0x36
	v_lshlrev_b32_e32 v1, 4, v1
	v_lshlrev_b32_e32 v2, 14, v132
	v_lshlrev_b32_e32 v5, 13, v133
	v_lshlrev_b32_e32 v6, 4, v6
	v_lshlrev_b32_e32 v8, 4, v8
	v_lshlrev_b32_e32 v0, 4, v0
	v_lshlrev_b32_e32 v3, 7, v188
	v_or_b32_e32 v4, v1, v2
	v_or_b32_e32 v1, v1, v5
	v_or_b32_e32 v7, v6, v2
	v_or_b32_e32 v6, v6, v5
	v_or_b32_e32 v9, v8, v2
	v_or_b32_e32 v8, v8, v5
	v_or_b32_e32 v2, v0, v2
	v_or_b32_e32 v0, v0, v5
	v_add_u32_e32 v134, v4, v3
	v_add_u32_e32 v135, v1, v3
	v_add_u32_e32 v136, v7, v3
	v_add_u32_e32 v137, v6, v3
	v_add_u32_e32 v138, v9, v3
	v_add_u32_e32 v139, v8, v3
	v_add_u32_e32 v140, v2, v3
	v_add_u32_e32 v141, v0, v3
	v_mov_b32_e32 v111, v161
	v_mov_b32_e32 v64, 0
	v_mov_b32_e32 v65, v161
	v_mov_b32_e32 v66, v161
	v_mov_b32_e32 v67, v161
	v_mov_b32_e32 v68, v161
	v_mov_b32_e32 v69, v161
	v_mov_b32_e32 v70, v161
	v_mov_b32_e32 v71, v161
	v_mov_b32_e32 v72, v161
	v_mov_b32_e32 v73, v161
	v_mov_b32_e32 v74, v161
	v_mov_b32_e32 v75, v161
	v_mov_b32_e32 v76, v161
	v_mov_b32_e32 v77, v161
	v_mov_b32_e32 v78, v161
	v_mov_b32_e32 v79, v161
	v_mov_b32_e32 v32, 0
	v_mov_b32_e32 v33, v161
	v_mov_b32_e32 v34, v161
	v_mov_b32_e32 v35, v161
	v_mov_b32_e32 v36, v161
	v_mov_b32_e32 v37, v161
	v_mov_b32_e32 v38, v161
	v_mov_b32_e32 v39, v161
	v_mov_b32_e32 v40, v161
	v_mov_b32_e32 v41, v161
	v_mov_b32_e32 v42, v161
	v_mov_b32_e32 v43, v161
	v_mov_b32_e32 v44, v161
	v_mov_b32_e32 v45, v161
	v_mov_b32_e32 v46, v161
	v_mov_b32_e32 v47, v161
	v_mov_b32_e32 v0, 0
	v_mov_b32_e32 v1, v161
	v_mov_b32_e32 v2, v161
	v_mov_b32_e32 v3, v161
	v_mov_b32_e32 v4, v161
	v_mov_b32_e32 v5, v161
	v_mov_b32_e32 v6, v161
	v_mov_b32_e32 v7, v161
	v_mov_b32_e32 v8, v161
	v_mov_b32_e32 v9, v161
	v_mov_b32_e32 v10, v161
	v_mov_b32_e32 v11, v161
	v_mov_b32_e32 v12, v161
	v_mov_b32_e32 v13, v161
	v_mov_b32_e32 v14, v161
	v_mov_b32_e32 v15, v161
	v_mov_b32_e32 v112, 0
	v_mov_b32_e32 v113, v161
	v_mov_b32_e32 v114, v161
	v_mov_b32_e32 v115, v161
	v_mov_b32_e32 v116, v161
	v_mov_b32_e32 v117, v161
	v_mov_b32_e32 v118, v161
	v_mov_b32_e32 v119, v161
	v_mov_b32_e32 v120, v161
	v_mov_b32_e32 v121, v161
	v_mov_b32_e32 v122, v161
	v_mov_b32_e32 v123, v161
	v_mov_b32_e32 v124, v161
	v_mov_b32_e32 v125, v161
	v_mov_b32_e32 v126, v161
	v_mov_b32_e32 v127, v161
	v_mov_b32_e32 v80, 0
	v_mov_b32_e32 v81, v161
	v_mov_b32_e32 v82, v161
	v_mov_b32_e32 v83, v161
	v_mov_b32_e32 v84, v161
	v_mov_b32_e32 v85, v161
	v_mov_b32_e32 v86, v161
	v_mov_b32_e32 v87, v161
	v_mov_b32_e32 v88, v161
	v_mov_b32_e32 v89, v161
	v_mov_b32_e32 v90, v161
	v_mov_b32_e32 v91, v161
	v_mov_b32_e32 v92, v161
	v_mov_b32_e32 v93, v161
	v_mov_b32_e32 v94, v161
	v_mov_b32_e32 v95, v161
	v_mov_b32_e32 v48, 0
	v_mov_b32_e32 v49, v161
	v_mov_b32_e32 v50, v161
	v_mov_b32_e32 v51, v161
	v_mov_b32_e32 v52, v161
	v_mov_b32_e32 v53, v161
	v_mov_b32_e32 v54, v161
	v_mov_b32_e32 v55, v161
	v_mov_b32_e32 v56, v161
	v_mov_b32_e32 v57, v161
	v_mov_b32_e32 v58, v161
	v_mov_b32_e32 v59, v161
	v_mov_b32_e32 v60, v161
	v_mov_b32_e32 v61, v161
	v_mov_b32_e32 v62, v161
	v_mov_b32_e32 v63, v161
	v_mov_b32_e32 v16, 0
	v_mov_b32_e32 v17, v161
	v_mov_b32_e32 v18, v161
	v_mov_b32_e32 v19, v161
	v_mov_b32_e32 v20, v161
	v_mov_b32_e32 v21, v161
	v_mov_b32_e32 v22, v161
	v_mov_b32_e32 v23, v161
	v_mov_b32_e32 v24, v161
	v_mov_b32_e32 v25, v161
	v_mov_b32_e32 v26, v161
	v_mov_b32_e32 v27, v161
	v_mov_b32_e32 v28, v161
	v_mov_b32_e32 v29, v161
	v_mov_b32_e32 v30, v161
	v_mov_b32_e32 v31, v161
	s_waitcnt lgkmcnt(0)
	s_barrier
